# attention unit 1: prologue de-serialisation - the selected-branch first two K/V tiles' global loads issued ~1900 instructions earlier (before the emit/top-k section), single drain before the LDS write
# speedup vs baseline: 1.0007x; 1.0007x over previous
; #define LAS __attribute__((address_space(3)))
; __device__ __forceinline__ unsigned cvt_pk_bf16(float lo, float hi) { unsigned r; asm volatile("v_cvt_pk_bf16_f32 %0, %1, %2" : "=v"(r) : "v"(lo), "v"(hi)); return r; }
; #define LDS_WAIT() asm volatile("s_waitcnt lgkmcnt(0)" ::: "memory")
; __device__ __forceinline__ int crow(int r, int hi) { return (r & 3) + 8 * (r >> 2) + 4 * hi; }
; template <int MODE>
; __device__ __forceinline__ void emit_scaled(const f32x16* o, float scl, LAS float* wsf, int r32, int hi, float* ya, bf16_t* yp) {
;     if (hi == 0) wsf[r32] = scl;
;     int oa = (4 * hi) * DATT + r32, ob = (4 * hi) * 64 + r32;
;     asm volatile("" : "+v"(oa), "+v"(ob));
;     float* yb = ya + oa; bf16_t* ypb = yp + ob;
;     float prev[16][4];
;     if (MODE >= 1) {
; #pragma unroll
;         for (int r = 0; r < 16; ++r) { const float* p = yb + (size_t)((r & 3) + 8 * (r >> 2)) * DATT;
; #pragma unroll
;             for (int d = 0; d < 4; ++d) prev[r][d] = p[d * 32]; }
;     }
;     LDS_WAIT();
;     float sv[16];
; #pragma unroll
;     for (int r = 0; r < 16; ++r) sv[r] = wsf[crow(r, hi)];
;     LDS_WAIT();
; #pragma unroll
;     for (int r = 0; r < 16; ++r) { const int orow = (r & 3) + 8 * (r >> 2);
;         float* p = yb + (size_t)orow * DATT; bf16_t* q = ypb + (size_t)orow * 64;
; #pragma unroll
;         for (int d = 0; d < 4; ++d) { float v = o[d][r] * sv[r];
;             if (MODE >= 1) v += prev[r][d];
;             if (MODE <= 1) p[d * 32] = v;
;             else { const float vn = __shfl_xor(v, 1); if ((r32 & 1) == 0) *(unsigned*)(q + (d >> 1) * (256 * 64) + (d & 1) * 32) = cvt_pk_bf16(v, vn); } } }
.LBB0_2781:
	s_or_b64 exec, exec, s[0:1]
	s_lshl_b32 s83, s8, 11
	s_add_i32 s77, s83, s76
	s_or_b32 s78, s77, s59
	s_lshl_b64 s[0:1], s[78:79], 13
	s_lshl_b32 s4, s67, 7
	v_lshl_or_b32 v152, v132, 13, v99
	v_lshl_or_b32 v150, v132, 8, v99
	v_ashrrev_i32_e32 v230, 4, v0
	v_lshlrev_b32_e32 v231, 3, v0
	v_and_b32_e32 v231, 0x78, v231
	v_lshlrev_b32_e32 v231, 1, v231
	v_lshl_add_u32 v230, v230, 8, v231
	v_add_u32_e32 v231, 0x2000, v230
	v_add_u32_e32 v232, 0x4000, v230
	v_add_u32_e32 v233, 0x6000, v230
	s_lshl_b32 s98, s63, 19
	v_readlane_b32 s99, v246, 38
	s_nop 1
	s_add_u32 s98, s99, s98
	v_readlane_b32 s99, v246, 39
	s_nop 1
	s_addc_u32 s99, s99, 0
	s_nop 0
	global_load_dwordx4 v[132:135], v230, s[98:99]
	global_load_dwordx4 v[136:139], v231, s[98:99]
	global_load_dwordx4 v[214:217], v232, s[98:99]
	global_load_dwordx4 v[218:221], v233, s[98:99]
	s_lshl_b32 s98, s63, 19
	v_readlane_b32 s99, v246, 36
	s_nop 1
	s_add_u32 s98, s99, s98
	v_readlane_b32 s99, v246, 37
	s_nop 1
	s_addc_u32 s99, s99, 0
	s_nop 0
	global_load_dwordx4 v[140:143], v230, s[98:99]
	global_load_dwordx4 v[144:147], v231, s[98:99]
	global_load_dwordx4 v[222:225], v232, s[98:99]
	global_load_dwordx4 v[226:229], v233, s[98:99]
	s_mov_b32 s5, s79
	s_add_u32 s0, s84, s0
	v_mov_b32_e32 v2, v150
	v_mov_b32_e32 v86, v152
	s_addc_u32 s1, s85, s1
	s_lshl_b64 s[4:5], s[4:5], 2
	s_waitcnt lgkmcnt(0)
	v_add_u32_e32 v149, s96, v96
	s_add_u32 s92, s0, s4
	ds_read_b128 v[70:73], v149
	ds_read_b128 v[74:77], v149 offset:32
	ds_read_b128 v[78:81], v149 offset:64
	ds_read_b128 v[82:85], v149 offset:96
	v_writelane_b32 v246, s4, 7
	s_addc_u32 s93, s1, s5
	v_ashrrev_i32_e32 v87, 31, v86
	v_lshl_add_u64 v[86:87], v[86:87], 2, s[92:93]
	s_waitcnt lgkmcnt(3)
	v_mul_f32_e32 v2, v4, v70
	s_waitcnt lgkmcnt(0)
	global_store_dword v[86:87], v2, off
	v_mul_f32_e32 v2, v20, v70
	global_store_dword v[86:87], v2, off offset:128
	v_mul_f32_e32 v2, v36, v70
	global_store_dword v[86:87], v2, off offset:256
	v_mul_f32_e32 v2, v52, v70
	v_add_co_u32_e32 v4, vcc, s25, v86
	global_store_dword v[86:87], v2, off offset:384
	v_mul_f32_e32 v2, v5, v71
	v_addc_co_u32_e32 v5, vcc, 0, v87, vcc
	global_store_dword v[4:5], v2, off
	v_mul_f32_e32 v2, v21, v71
	global_store_dword v[4:5], v2, off offset:128
	v_mul_f32_e32 v2, v37, v71
	global_store_dword v[4:5], v2, off offset:256
	v_mul_f32_e32 v2, v53, v71
	global_store_dword v[4:5], v2, off offset:384
	v_add_co_u32_e32 v4, vcc, s21, v86
	v_mul_f32_e32 v2, v6, v72
	s_nop 0
	v_addc_co_u32_e32 v5, vcc, 0, v87, vcc
	global_store_dword v[4:5], v2, off
	v_mul_f32_e32 v2, v22, v72
	global_store_dword v[4:5], v2, off offset:128
	v_mul_f32_e32 v2, v38, v72
	global_store_dword v[4:5], v2, off offset:256
	v_mul_f32_e32 v2, v54, v72
	global_store_dword v[4:5], v2, off offset:384
	v_add_co_u32_e32 v4, vcc, s27, v86
	v_mul_f32_e32 v2, v7, v73
	s_nop 0
	v_addc_co_u32_e32 v5, vcc, 0, v87, vcc
	global_store_dword v[4:5], v2, off
	v_mul_f32_e32 v2, v23, v73
	global_store_dword v[4:5], v2, off offset:128
	v_mul_f32_e32 v2, v39, v73
	global_store_dword v[4:5], v2, off offset:256
	v_mul_f32_e32 v2, v55, v73
	global_store_dword v[4:5], v2, off offset:384
	v_add_co_u32_e32 v4, vcc, s23, v86
	s_waitcnt lgkmcnt(2)
	v_mul_f32_e32 v2, v8, v74
	v_addc_co_u32_e32 v5, vcc, 0, v87, vcc
	global_store_dword v[4:5], v2, off
	v_mul_f32_e32 v2, v24, v74
	global_store_dword v[4:5], v2, off offset:128
	v_mul_f32_e32 v2, v40, v74
	global_store_dword v[4:5], v2, off offset:256
	v_mul_f32_e32 v2, v56, v74
	global_store_dword v[4:5], v2, off offset:384
	v_add_co_u32_e32 v4, vcc, s28, v86
	v_mul_f32_e32 v2, v9, v75
	s_nop 0
	v_addc_co_u32_e32 v5, vcc, 0, v87, vcc
	global_store_dword v[4:5], v2, off
	v_mul_f32_e32 v2, v25, v75
	global_store_dword v[4:5], v2, off offset:128
	v_mul_f32_e32 v2, v41, v75
	global_store_dword v[4:5], v2, off offset:256
	v_mul_f32_e32 v2, v57, v75
	global_store_dword v[4:5], v2, off offset:384
	v_add_co_u32_e32 v4, vcc, s58, v86
	v_mul_f32_e32 v2, v10, v76
	s_nop 0
	v_addc_co_u32_e32 v5, vcc, 0, v87, vcc
	global_store_dword v[4:5], v2, off
	v_mul_f32_e32 v2, v26, v76
	global_store_dword v[4:5], v2, off offset:128
	v_mul_f32_e32 v2, v42, v76
	global_store_dword v[4:5], v2, off offset:256
	v_mul_f32_e32 v2, v58, v76
	global_store_dword v[4:5], v2, off offset:384
	v_add_co_u32_e32 v4, vcc, s29, v86
	v_mul_f32_e32 v2, v11, v77
	s_nop 0
	v_addc_co_u32_e32 v5, vcc, 0, v87, vcc
	global_store_dword v[4:5], v2, off
	v_mul_f32_e32 v2, v27, v77
	global_store_dword v[4:5], v2, off offset:128
	v_mul_f32_e32 v2, v43, v77
	global_store_dword v[4:5], v2, off offset:256
	v_mul_f32_e32 v2, v59, v77
	global_store_dword v[4:5], v2, off offset:384
	v_add_co_u32_e32 v4, vcc, s30, v86
	s_waitcnt lgkmcnt(1)
	v_mul_f32_e32 v2, v12, v78
	v_addc_co_u32_e32 v5, vcc, 0, v87, vcc
	global_store_dword v[4:5], v2, off
	v_mul_f32_e32 v2, v28, v78
	global_store_dword v[4:5], v2, off offset:128
	v_mul_f32_e32 v2, v44, v78
	global_store_dword v[4:5], v2, off offset:256
	v_mul_f32_e32 v2, v60, v78
	global_store_dword v[4:5], v2, off offset:384
	v_add_co_u32_e32 v4, vcc, s31, v86
	v_mul_f32_e32 v2, v13, v79
	s_nop 0
	v_addc_co_u32_e32 v5, vcc, 0, v87, vcc
	global_store_dword v[4:5], v2, off
	v_mul_f32_e32 v2, v29, v79
	global_store_dword v[4:5], v2, off offset:128
	v_mul_f32_e32 v2, v45, v79
	global_store_dword v[4:5], v2, off offset:256
	v_mul_f32_e32 v2, v61, v79
	global_store_dword v[4:5], v2, off offset:384
	v_add_co_u32_e32 v4, vcc, s34, v86
	v_mul_f32_e32 v2, v14, v80
	s_nop 0
	v_addc_co_u32_e32 v5, vcc, 0, v87, vcc
	global_store_dword v[4:5], v2, off
	v_mul_f32_e32 v2, v30, v80
	global_store_dword v[4:5], v2, off offset:128
	v_mul_f32_e32 v2, v46, v80
	global_store_dword v[4:5], v2, off offset:256
	v_mul_f32_e32 v2, v62, v80
	global_store_dword v[4:5], v2, off offset:384
	v_add_co_u32_e32 v4, vcc, s35, v86
	v_mul_f32_e32 v2, v15, v81
	s_nop 0
	v_addc_co_u32_e32 v5, vcc, 0, v87, vcc
	global_store_dword v[4:5], v2, off
	v_mul_f32_e32 v2, v31, v81
	global_store_dword v[4:5], v2, off offset:128
	v_mul_f32_e32 v2, v47, v81
	global_store_dword v[4:5], v2, off offset:256
	v_mul_f32_e32 v2, v63, v81
	global_store_dword v[4:5], v2, off offset:384
	v_add_co_u32_e32 v4, vcc, s36, v86
	s_waitcnt lgkmcnt(0)
; __device__ __forceinline__ unsigned cvt_pk_bf16(float lo, float hi) { unsigned r; asm volatile("v_cvt_pk_bf16_f32 %0, %1, %2" : "=v"(r) : "v"(lo), "v"(hi)); return r; }
; template <int MODE>
; __device__ __forceinline__ void emit_scaled(const f32x16* o, float scl, LAS float* wsf, int r32, int hi, float* ya, bf16_t* yp) {
;     ...
;     for (int r = 0; r < 16; ++r) { const int orow = (r & 3) + 8 * (r >> 2);
;         float* p = yb + (size_t)orow * DATT; bf16_t* q = ypb + (size_t)orow * 64;
; #pragma unroll
;         for (int d = 0; d < 4; ++d) { float v = o[d][r] * sv[r];
;             if (MODE >= 1) v += prev[r][d];
;             if (MODE <= 1) p[d * 32] = v;
;             else { const float vn = __shfl_xor(v, 1); if ((r32 & 1) == 0) *(unsigned*)(q + (d >> 1) * (256 * 64) + (d & 1) * 32) = cvt_pk_bf16(v, vn); } } }
; __device__ __forceinline__ void attn_unit(Frame& F, int b, int g, int sb) {
;     ...
;     __syncthreads();
;     {
;         const int rw = tid >> 3, jg = tid & 7;
; #pragma unroll
;         for (int e = 0; e < 4; ++e) { const int j = 4 * jg + e; impS[rw * 33 + j] = (impH[(0 * 64 + rw) * 33 + j] + impH[(1 * 64 + rw) * 33 + j]) + (impH[(2 * 64 + rw) * 33 + j] + impH[(3 * 64 + rw) * 33 + j]); }
;         __syncthreads();
;         unsigned bits = 0u;
;         if (sb <= 7) {
; #pragma unroll
;             for (int e = 0; e < 4; ++e) { const int j = 4 * jg + e; if (j <= sb) bits |= 1u << j; }
;         } else {
;             float v[32];
; #pragma unroll
;             for (int i = 0; i < 32; ++i) v[i] = impS[rw * 33 + i];
; #pragma unroll
;             for (int e = 0; e < 4; ++e) { const int j = 4 * jg + e; float vj = 0.f;
; #pragma unroll
;                 for (int i = 0; i < 32; ++i) vj = (i == j) ? v[i] : vj;
;                 int rank = 0;
; #pragma unroll
;                 for (int i = 1; i < 32; ++i) { const bool cand = i <= sb - 2; rank += (cand && (v[i] > vj || (v[i] == vj && i < j))) ? 1 : 0; }
	v_mul_f32_e32 v2, v16, v82
	v_addc_co_u32_e32 v5, vcc, 0, v87, vcc
	global_store_dword v[4:5], v2, off
	v_mul_f32_e32 v2, v32, v82
	global_store_dword v[4:5], v2, off offset:128
	v_mul_f32_e32 v2, v48, v82
	global_store_dword v[4:5], v2, off offset:256
	v_mul_f32_e32 v2, v64, v82
	global_store_dword v[4:5], v2, off offset:384
	v_add_co_u32_e32 v4, vcc, s37, v86
	v_mul_f32_e32 v2, v17, v83
	s_nop 0
	v_addc_co_u32_e32 v5, vcc, 0, v87, vcc
	global_store_dword v[4:5], v2, off
	v_mul_f32_e32 v2, v33, v83
	global_store_dword v[4:5], v2, off offset:128
	v_mul_f32_e32 v2, v49, v83
	global_store_dword v[4:5], v2, off offset:256
	v_mul_f32_e32 v2, v65, v83
	global_store_dword v[4:5], v2, off offset:384
	v_add_co_u32_e32 v4, vcc, s50, v86
	v_mul_f32_e32 v2, v18, v84
	s_nop 0
	v_addc_co_u32_e32 v5, vcc, 0, v87, vcc
	global_store_dword v[4:5], v2, off
	v_mul_f32_e32 v2, v34, v84
	global_store_dword v[4:5], v2, off offset:128
	v_mul_f32_e32 v2, v50, v84
	global_store_dword v[4:5], v2, off offset:256
	v_mul_f32_e32 v2, v66, v84
	global_store_dword v[4:5], v2, off offset:384
	v_add_co_u32_e32 v4, vcc, s51, v86
	v_mul_f32_e32 v2, v19, v85
	s_nop 0
	v_addc_co_u32_e32 v5, vcc, 0, v87, vcc
	global_store_dword v[4:5], v2, off
	v_mul_f32_e32 v2, v35, v85
	global_store_dword v[4:5], v2, off offset:128
	v_mul_f32_e32 v2, v51, v85
	global_store_dword v[4:5], v2, off offset:256
	v_mul_f32_e32 v2, v67, v85
	global_store_dword v[4:5], v2, off offset:384
	v_ashrrev_i32_e32 v2, 3, v148
	v_mul_lo_u32 v39, v2, s24
	v_and_b32_e32 v68, 7, v148
	v_add_u32_e32 v6, s26, v39
	v_lshl_add_u32 v7, v68, 4, v6
	s_waitcnt vmcnt(63) expcnt(7) lgkmcnt(15)
	s_barrier
	ds_read2st64_b32 v[4:5], v7 offset1:33
	ds_read_b32 v8, v7 offset:16896
	ds_read_b32 v9, v7 offset:25344
	v_lshlrev_b32_e32 v34, 2, v68
	v_lshl_add_u32 v10, v2, 5, v2
	v_add_u32_e32 v11, v34, v10
	s_waitcnt lgkmcnt(2)
	v_add_f32_e32 v4, v4, v5
	s_waitcnt lgkmcnt(0)
	v_add_f32_e32 v5, v8, v9
	v_add_f32_e32 v4, v4, v5
	v_lshl_add_u32 v5, v11, 2, s47
	v_or_b32_e32 v35, 1, v34
	ds_write_b32 v5, v4
	v_lshl_add_u32 v4, v35, 2, v6
	ds_read_b32 v4, v4
	ds_read_b32 v5, v7 offset:8452
	ds_read_b32 v8, v7 offset:16900
	ds_read_b32 v9, v7 offset:25348
	v_add_u32_e32 v11, v35, v10
	v_or_b32_e32 v36, 2, v34
	s_waitcnt lgkmcnt(2)
	v_add_f32_e32 v4, v4, v5
	v_or_b32_e32 v37, 3, v34
	s_waitcnt lgkmcnt(0)
	v_add_f32_e32 v5, v8, v9
	v_add_f32_e32 v4, v4, v5
	v_lshl_add_u32 v5, v11, 2, s47
	ds_write_b32 v5, v4
	v_lshl_add_u32 v4, v36, 2, v6
	ds_read_b32 v4, v4
	ds_read_b32 v5, v7 offset:8456
	ds_read_b32 v8, v7 offset:16904
	ds_read_b32 v9, v7 offset:25352
	v_add_u32_e32 v11, v36, v10
	v_add_u32_e32 v38, s47, v39
	s_waitcnt lgkmcnt(2)
	v_add_f32_e32 v4, v4, v5
	v_writelane_b32 v246, s5, 8
	s_waitcnt lgkmcnt(0)
	v_add_f32_e32 v5, v8, v9
	v_add_f32_e32 v4, v4, v5
	v_lshl_add_u32 v5, v11, 2, s47
	ds_write_b32 v5, v4
	v_lshl_add_u32 v4, v37, 2, v6
	ds_read_b32 v4, v4
	ds_read_b32 v5, v7 offset:8460
	ds_read_b32 v6, v7 offset:16908
	ds_read_b32 v7, v7 offset:25356
	v_add_u32_e32 v8, v37, v10
	v_cmp_eq_u32_e64 s[4:5], 0, v68
	s_waitcnt lgkmcnt(2)
	v_add_f32_e32 v4, v4, v5
	v_mov_b32_e32 v40, 0
	s_waitcnt lgkmcnt(0)
	v_add_f32_e32 v5, v6, v7
	v_add_f32_e32 v4, v4, v5
	v_lshl_add_u32 v5, v8, 2, s47
	ds_write_b32 v5, v4
	s_waitcnt lgkmcnt(0)
	s_barrier
	ds_read2_b32 v[16:17], v38 offset0:1 offset1:2
	ds_read2_b32 v[14:15], v38 offset0:3 offset1:4
	ds_read2_b32 v[12:13], v38 offset0:5 offset1:6
	ds_read2_b32 v[10:11], v38 offset0:7 offset1:8
	ds_read2_b32 v[8:9], v38 offset0:9 offset1:10
	ds_read2_b32 v[6:7], v38 offset0:11 offset1:12
	ds_read2_b32 v[4:5], v38 offset0:13 offset1:14
	ds_read2_b32 v[32:33], v38 offset0:15 offset1:16
	ds_read2_b32 v[30:31], v38 offset0:17 offset1:18
	ds_read2_b32 v[28:29], v38 offset0:19 offset1:20
	ds_read2_b32 v[26:27], v38 offset0:21 offset1:22
	ds_read2_b32 v[24:25], v38 offset0:23 offset1:24
	ds_read2_b32 v[22:23], v38 offset0:25 offset1:26
	ds_read2_b32 v[20:21], v38 offset0:27 offset1:28
	ds_read2_b32 v[18:19], v38 offset0:29 offset1:30
	ds_read_b32 v50, v38 offset:124
	v_mov_b32_e32 v38, 0
	s_and_saveexec_b64 s[0:1], s[4:5]
	v_add_u32_e32 v39, 0, v39
	v_add_u32_e32 v39, 0x16800, v39
	ds_read_b32 v40, v39
	s_or_b64 exec, exec, s[0:1]
	v_cmp_eq_u32_e64 s[10:11], 1, v68
	v_cmp_eq_u32_e64 s[12:13], 2, v68
	v_cmp_eq_u32_e64 s[14:15], 3, v68
	s_waitcnt lgkmcnt(0)
	v_cndmask_b32_e64 v39, v40, v15, s[10:11]
	v_cndmask_b32_e64 v39, v39, v11, s[12:13]
	v_cndmask_b32_e64 v39, v39, v7, s[14:15]
	v_cmp_eq_u32_e64 s[16:17], 4, v68
	v_cmp_eq_u32_e64 s[18:19], 5, v68
	v_cmp_eq_u32_e64 s[20:21], 6, v68
	v_cndmask_b32_e64 v39, v39, v33, s[16:17]
	v_cndmask_b32_e64 v39, v39, v29, s[18:19]
	v_cndmask_b32_e64 v39, v39, v25, s[20:21]
	v_cmp_eq_u32_e64 s[8:9], 7, v68
	s_cmp_gt_u32 s71, 16
	s_cselect_b64 s[24:25], -1, 0
	v_cndmask_b32_e64 v39, v39, v21, s[8:9]
	s_cmp_lt_u32 s71, 17
	v_cmp_lt_u32_e64 s[6:7], 3, v68
	s_cbranch_scc1 .LBB0_2787
	v_cmp_ngt_f32_e32 vcc, v32, v39
	v_mov_b32_e32 v38, 1
	s_and_saveexec_b64 s[0:1], vcc
	v_cmp_eq_f32_e32 vcc, v32, v39
	s_and_b64 s[22:23], vcc, s[6:7]
	v_cndmask_b32_e64 v38, 0, 1, s[22:23]
	s_or_b64 exec, exec, s[0:1]

; #define LAS __attribute__((address_space(3)))
; __device__ __forceinline__ int v_st(int k, int c) { const int kk = (k & ~0xC) | ((k & 4) << 1) | ((k & 8) >> 1); return ((kk >> 3) * 4 + (c >> 5)) * 512 + ((kk & 7) * 32 + (c & 31)) * 2; }
; __device__ __forceinline__ void tile_write(const TileStage& T, LAS unsigned char* lds, int kbuf, int vbuf, int sr, int sc) {
;     const int kws = KSWZ(sr, sc * 2);
;     *(LAS bf16x8*)(lds + AT_K + kbuf * SHM_T + kws) = T.k0; *(LAS bf16x8*)(lds + AT_K + kbuf * SHM_T + kws + 32 * 256) = T.k1;
;     *(LAS bf16x8*)(lds + AT_V + vbuf * SHM_T + v_st(sr, sc)) = T.v0; *(LAS bf16x8*)(lds + AT_V + vbuf * SHM_T + v_st(32 + sr, sc)) = T.v1;
; }
; template <int MODE>
; __device__ __forceinline__ void attn_branch(Frame& F, const bf16_t* Kp, const bf16_t* Vp, int j_lo, int j_hi, int sb, const bf16x8* qr, unsigned smask, f32x16* o, float& l_out) {
;     ...
;     const int qpos = 64 * sb + 32 * rh + r32;
;     float m_reg = -1e30f, l_reg = 0.f;
; #pragma unroll
;     for (int d = 0; d < 4; ++d) o[d] = f32x16{};
;     const int NT = j_hi - j_lo + 1;
;     TileStage T;
;     { TileStage T1; tile_load(T, Kp, Vp, j_lo * 64, sr, sc); if (NT > 1) tile_load(T1, Kp, Vp, (j_lo + 1) * 64, sr, sc);
;       tile_write(T, lds, 0, 0, sr, sc); if (NT > 1) tile_write(T1, lds, 1, 1, sr, sc); }
;     __syncthreads();
.LBB0_3057:
	s_or_b64 exec, exec, s[0:1]
	s_lshl_b32 s6, s63, 18
	s_lshl_b32 s0, s63, 19
	v_readlane_b32 s1, v246, 36
	v_lshl_add_u32 v2, v153, 2, 0
	s_add_u32 s42, s1, s0
	v_readlane_b32 s1, v246, 37
	v_add_u32_e32 v2, 0x16700, v2
	v_mov_b32_e32 v24, v0
	s_addc_u32 s43, s1, 0
	v_readlane_b32 s1, v246, 38
	s_waitcnt lgkmcnt(0)
	s_barrier
	ds_read_b32 v160, v2
	s_add_u32 s44, s1, s0
	v_ashrrev_i32_e32 v20, 4, v24
	v_readlane_b32 s0, v246, 39
	v_lshlrev_b32_e32 v25, 3, v24
	v_ashrrev_i32_e32 v21, 31, v20
	v_add_u32_e32 v22, 32, v20
	s_addc_u32 s45, s0, 0
	v_and_b32_e32 v2, 0x78, v25
	v_lshlrev_b64 v[4:5], 8, v[20:21]
	v_ashrrev_i32_e32 v23, 31, v22
	v_lshl_add_u64 v[6:7], s[44:45], 0, v[4:5]
	v_lshlrev_b32_e32 v2, 1, v2
	v_lshlrev_b64 v[8:9], 8, v[22:23]
	v_lshl_add_u64 v[6:7], v[6:7], 0, v[2:3]
	v_lshl_add_u64 v[10:11], s[44:45], 0, v[8:9]
	s_mov_b64 s[0:1], 0x4000
	v_lshl_add_u64 v[10:11], v[10:11], 0, v[2:3]
	v_lshl_add_u64 v[6:7], s[42:43], 0, v[4:5]
	v_lshl_add_u64 v[12:13], v[4:5], 0, s[0:1]
	s_mov_b64 s[0:1], 0x6000
	v_lshl_add_u64 v[6:7], v[6:7], 0, v[2:3]
	v_lshl_add_u64 v[8:9], s[42:43], 0, v[8:9]
	v_lshl_add_u64 v[14:15], v[4:5], 0, s[0:1]
	v_lshl_add_u64 v[8:9], v[8:9], 0, v[2:3]
	v_lshl_add_u64 v[6:7], s[44:45], 0, v[12:13]
	v_lshl_add_u64 v[4:5], s[44:45], 0, v[14:15]
	v_lshl_add_u64 v[12:13], s[42:43], 0, v[12:13]
	v_lshl_add_u64 v[14:15], s[42:43], 0, v[14:15]
	v_lshl_add_u64 v[6:7], v[6:7], 0, v[2:3]
	v_lshl_add_u64 v[8:9], v[4:5], 0, v[2:3]
	v_lshl_add_u64 v[12:13], v[12:13], 0, v[2:3]
	v_lshl_add_u64 v[16:17], v[14:15], 0, v[2:3]
	s_nop 0
	s_nop 0
	s_nop 0
	v_and_b32_e32 v30, 0xfffff0, v20
	v_lshlrev_b32_e32 v31, 1, v20
	v_lshrrev_b32_e32 v32, 1, v20
	v_and_b32_e32 v34, 3, v20
	v_and_or_b32 v30, v31, 8, v30
	v_and_or_b32 v31, v32, 4, v34
	v_and_b32_e32 v32, 0xfffff0, v22
	v_lshlrev_b32_e32 v22, 1, v22
	v_and_or_b32 v22, v22, 8, v32
	v_bfe_u32 v33, v25, 5, 2
	v_lshrrev_b32_e32 v30, 1, v30
	v_lshrrev_b32_e32 v22, 1, v22
	v_lshlrev_b32_e32 v161, 8, v20
	v_bitop3_b32 v167, v2, v24, s69 bitop3:0x78
	v_or_b32_e32 v30, v30, v33
	v_or_b32_e32 v22, v22, v33
	v_and_b32_e32 v23, 31, v24
	v_bfe_u32 v28, v24, 5, 1
	v_and_b32_e32 v168, 48, v2
	v_lshl_add_u32 v169, v31, 6, 0
	v_add3_u32 v31, 0, v161, v167
	v_lshlrev_b32_e32 v170, 9, v30
	v_lshlrev_b32_e32 v171, 9, v22
	v_lshlrev_b32_e32 v26, 4, v24
	v_add3_u32 v32, s62, v161, v167
	v_add3_u32 v30, v169, v170, v168
	v_add3_u32 v22, v169, v171, v168
	v_lshl_add_u64 v[154:155], s[44:45], 0, v[2:3]
	v_lshl_add_u64 v[156:157], s[42:43], 0, v[2:3]
	v_lshlrev_b32_e32 v2, 8, v23
	v_lshlrev_b32_e32 v27, 1, v24
	v_and_b32_e32 v27, 32, v27
	s_movk_i32 s0, 0x118
	s_lshl_b32 s52, s75, 8
	v_and_b32_e32 v21, 63, v24
	v_and_b32_e32 v29, 0xc0, v26
	v_cmp_gt_u32_e64 s[4:5], 32, v21
	v_add_u32_e32 v158, 0xa0, v20
	s_mov_b32 s7, 0
	v_mov_b32_e32 v181, 0
	s_waitcnt vmcnt(0)
	ds_write_b128 v31, v[132:135] offset:49152
	ds_write_b128 v31, v[136:139] offset:57344
	ds_write_b128 v30, v[140:143]
	ds_write_b128 v22, v[144:147]
	ds_write_b128 v32, v[214:217]
	ds_write_b128 v32, v[218:221] offset:8192
	ds_write_b128 v30, v[222:225] offset:16384
	ds_write_b128 v22, v[226:229] offset:16384
	v_lshlrev_b32_e32 v4, 4, v28
	v_bitop3_b32 v6, v28, v24, 7 bitop3:0x78
	v_and_b32_e32 v5, 0x70, v26
	v_lshl_or_b32 v172, v6, 4, v2
	v_or_b32_e32 v6, 32, v4
	v_bitop3_b32 v173, v6, v2, v5 bitop3:0xde
	v_or_b32_e32 v6, 64, v4
	v_bitop3_b32 v174, v6, v2, v5 bitop3:0xde
	v_or_b32_e32 v6, 0x60, v4
	v_bitop3_b32 v175, v6, v2, v5 bitop3:0xde
	v_lshlrev_b32_e32 v5, 2, v23
	v_and_or_b32 v6, v25, s0, v27
	v_readlane_b32 s0, v246, 41
	v_add_u32_e32 v176, s96, v5
	v_add_u32_e32 v177, s96, v4
	v_add_u32_e32 v5, s0, v5
	v_sub_u32_e32 v4, v5, v4
	v_lshlrev_b32_e32 v2, 2, v28
	v_subrev_u32_e32 v179, s52, v4
	v_add_u32_e32 v4, s59, v23
	v_mov_b32_e32 v16, v3
	v_mov_b32_e32 v17, v3
	v_add3_u32 v178, v29, 0, v6
	v_sub_u32_e32 v180, v4, v2
	v_mov_b32_e32 v2, v3
	v_mov_b32_e32 v4, v3
	v_mov_b32_e32 v5, v3
	v_mov_b32_e32 v6, v3
	v_mov_b32_e32 v7, v3
	v_mov_b32_e32 v8, v3
	v_mov_b32_e32 v9, v3
	v_mov_b32_e32 v10, v3
	v_mov_b32_e32 v11, v3
	v_mov_b32_e32 v12, v3
	v_mov_b32_e32 v13, v3
	v_mov_b32_e32 v14, v3
	v_mov_b32_e32 v15, v3
	v_mov_b64_e32 v[66:67], v[16:17]
	v_mov_b64_e32 v[50:51], v[16:17]
	v_mov_b64_e32 v[34:35], v[16:17]
	v_mov_b64_e32 v[64:65], v[14:15]
	v_mov_b64_e32 v[62:63], v[12:13]
	v_mov_b64_e32 v[60:61], v[10:11]
	v_mov_b64_e32 v[58:59], v[8:9]
	v_mov_b64_e32 v[56:57], v[6:7]
	v_mov_b64_e32 v[54:55], v[4:5]
	v_mov_b64_e32 v[52:53], v[2:3]
	v_mov_b64_e32 v[48:49], v[14:15]
	v_mov_b64_e32 v[46:47], v[12:13]
	v_mov_b64_e32 v[44:45], v[10:11]
	v_mov_b64_e32 v[42:43], v[8:9]
	v_mov_b64_e32 v[40:41], v[6:7]
	v_mov_b64_e32 v[38:39], v[4:5]
	v_mov_b64_e32 v[36:37], v[2:3]
	v_mov_b64_e32 v[32:33], v[14:15]
	v_mov_b64_e32 v[30:31], v[12:13]
	v_mov_b64_e32 v[28:29], v[10:11]
	v_mov_b64_e32 v[26:27], v[8:9]
	v_mov_b64_e32 v[24:25], v[6:7]
	v_mov_b64_e32 v[22:23], v[4:5]
	v_mov_b64_e32 v[20:21], v[2:3]
	v_mov_b64_e32 v[18:19], v[16:17]
	v_mov_b32_e32 v159, 0xf149f2ca
	s_movk_i32 s9, 0xffe0
	v_mov_b64_e32 v[16:17], v[14:15]
	v_mov_b64_e32 v[14:15], v[12:13]
	v_mov_b64_e32 v[12:13], v[10:11]
	v_mov_b64_e32 v[10:11], v[8:9]
	v_mov_b64_e32 v[8:9], v[6:7]
	v_mov_b64_e32 v[6:7], v[4:5]
	v_mov_b64_e32 v[4:5], v[2:3]
	s_mov_b32 s10, 0
	s_waitcnt lgkmcnt(0)
	s_barrier
